# GQA latent attention tile loop rewritten by hand: quarter-step software pipeline (QK of next quarter + PV of current interleaved with softmax VALU), barrier moved to tile boundary inside the step
# speedup vs baseline: 1.0551x; 1.0032x over previous
; DI float shx(float v, int mask, int lane) { return __int_as_float(__builtin_amdgcn_ds_bpermute((lane ^ mask) << 2, __float_as_int(v))); }
; DI unsigned pk2(float a, float b) { f2_t v = {a, b}; bf2_t r = __builtin_convertvector(v, bf2_t); return __builtin_bit_cast(unsigned, r); }
; DI void gqa_block2(unsigned char* lds, const int tid, const u16* __restrict__ q, const unsigned char* __restrict__ kimg, ...
;     ...
; #pragma unroll
;   for (int qt = 0; qt < 2; ++qt) {
;     const float lsum = ls[qt][0] + ls[qt][1];
;     const float inv = 1.f / (lsum + shx(lsum, 32, lane));
;     u16* ob = out + (size_t)(qt * 32 + ql) * DM;
;     u32x2 w0_[4], w1_[4];
; #pragma unroll
;     for (int j = 0; j < 4; ++j) {
;       w0_[j][0] = pk2(o[qt][0][4 * j] * inv, o[qt][0][4 * j + 1] * inv); w0_[j][1] = pk2(o[qt][0][4 * j + 2] * inv, o[qt][0][4 * j + 3] * inv);
;       w1_[j][0] = pk2(o[qt][1][4 * j] * inv, o[qt][1][4 * j + 1] * inv); w1_[j][1] = pk2(o[qt][1][4 * j + 2] * inv, o[qt][1][4 * j + 3] * inv);
;     }
;     store_ot_tile(ob, w0_, hl);
;     store_ot_tile(ob + 32, w1_, hl);
;   }
;   asm volatile("s_waitcnt vmcnt(0)" ::: "memory");
;   __builtin_amdgcn_s_barrier();
.LBB0_317:
	ds_bpermute_b32 v68, v233, v0
	s_waitcnt lgkmcnt(0)
	v_add_f32_e32 v0, v0, v68
	v_div_scale_f32 v68, s[4:5], v0, v0, 1.0
	v_rcp_f32_e32 v69, v68
	s_nop 0
	v_fma_f32 v70, -v68, v69, 1.0
	v_fmac_f32_e32 v69, v70, v69
	v_div_scale_f32 v70, vcc, 1.0, v0, 1.0
	v_mul_f32_e32 v71, v70, v69
	v_fma_f32 v72, -v68, v71, v70
	v_fmac_f32_e32 v71, v72, v69
	v_fma_f32 v68, -v68, v71, v70
	v_div_fmas_f32 v68, v68, v69, v71
	v_div_fixup_f32 v0, v68, v0, 1.0
	v_pk_mul_f32 v[34:35], v[34:35], v[0:1] op_sel_hi:[1,0]
	v_pk_mul_f32 v[36:37], v[36:37], v[0:1] op_sel_hi:[1,0]
	v_pk_mul_f32 v[50:51], v[50:51], v[0:1] op_sel_hi:[1,0]
	v_pk_mul_f32 v[52:53], v[52:53], v[0:1] op_sel_hi:[1,0]
	v_cvt_pk_bf16_f32 v34, v34, v35
	v_cvt_pk_bf16_f32 v35, v36, v37
	v_pk_mul_f32 v[36:37], v[54:55], v[0:1] op_sel_hi:[1,0]
	v_cvt_pk_bf16_f32 v50, v50, v51
	v_cvt_pk_bf16_f32 v51, v52, v53
	v_cvt_pk_bf16_f32 v52, v36, v37
	v_pk_mul_f32 v[36:37], v[56:57], v[0:1] op_sel_hi:[1,0]
	s_nop 0
	v_permlane32_swap_b32_e32 v50, v52
	v_cvt_pk_bf16_f32 v53, v36, v37
	v_pk_mul_f32 v[36:37], v[38:39], v[0:1] op_sel_hi:[1,0]
	v_pk_mul_f32 v[38:39], v[40:41], v[0:1] op_sel_hi:[1,0]
	v_cvt_pk_bf16_f32 v36, v36, v37
	v_cvt_pk_bf16_f32 v37, v38, v39
	v_pk_mul_f32 v[38:39], v[58:59], v[0:1] op_sel_hi:[1,0]
	v_pk_mul_f32 v[40:41], v[60:61], v[0:1] op_sel_hi:[1,0]
	v_cvt_pk_bf16_f32 v38, v38, v39
	v_cvt_pk_bf16_f32 v39, v40, v41
	v_pk_mul_f32 v[40:41], v[42:43], v[0:1] op_sel_hi:[1,0]
	v_permlane32_swap_b32_e32 v34, v36
	v_cvt_pk_bf16_f32 v42, v40, v41
	v_pk_mul_f32 v[40:41], v[44:45], v[0:1] op_sel_hi:[1,0]
	v_pk_mul_f32 v[44:45], v[64:65], v[0:1] op_sel_hi:[1,0]
	v_cvt_pk_bf16_f32 v43, v40, v41
	v_pk_mul_f32 v[40:41], v[62:63], v[0:1] op_sel_hi:[1,0]
	v_permlane32_swap_b32_e32 v35, v37
	v_cvt_pk_bf16_f32 v40, v40, v41
	v_cvt_pk_bf16_f32 v41, v44, v45
	v_pk_mul_f32 v[44:45], v[46:47], v[0:1] op_sel_hi:[1,0]
	v_pk_mul_f32 v[46:47], v[48:49], v[0:1] op_sel_hi:[1,0]
	v_lshlrev_b32_e32 v0, 11, v149
	v_cvt_pk_bf16_f32 v44, v44, v45
	v_cvt_pk_bf16_f32 v45, v46, v47
	v_lshl_add_u64 v[46:47], s[2:3], 0, v[0:1]
	v_lshlrev_b32_e32 v0, 1, v148
	v_lshl_add_u64 v[46:47], v[46:47], 0, v[0:1]
	v_add_f32_e32 v0, v66, v67
	global_store_dwordx4 v[46:47], v[34:37], off offset:1088
	ds_bpermute_b32 v34, v233, v0
	v_permlane32_swap_b32_e32 v38, v40
	v_permlane32_swap_b32_e32 v39, v41
	s_waitcnt lgkmcnt(0)
	v_add_f32_e32 v0, v0, v34
	v_div_scale_f32 v34, s[2:3], v0, v0, 1.0
	v_rcp_f32_e32 v35, v34
	global_store_dwordx4 v[46:47], v[38:41], off offset:1056
	s_mov_b64 s[2:3], 0x10400
	v_permlane32_swap_b32_e32 v51, v53
	v_fma_f32 v36, -v34, v35, 1.0
	v_fmac_f32_e32 v35, v36, v35
	v_div_scale_f32 v36, vcc, 1.0, v0, 1.0
	v_mul_f32_e32 v37, v36, v35
	v_fma_f32 v38, -v34, v37, v36
	v_fmac_f32_e32 v37, v38, v35
	v_fma_f32 v34, -v34, v37, v36
	v_div_fmas_f32 v34, v34, v35, v37
	v_div_fixup_f32 v0, v34, v0, 1.0
	v_pk_mul_f32 v[2:3], v[2:3], v[0:1] op_sel_hi:[1,0]
	v_pk_mul_f32 v[4:5], v[4:5], v[0:1] op_sel_hi:[1,0]
	v_pk_mul_f32 v[18:19], v[18:19], v[0:1] op_sel_hi:[1,0]
	v_pk_mul_f32 v[20:21], v[20:21], v[0:1] op_sel_hi:[1,0]
	v_cvt_pk_bf16_f32 v2, v2, v3
	v_cvt_pk_bf16_f32 v3, v4, v5
	v_pk_mul_f32 v[4:5], v[22:23], v[0:1] op_sel_hi:[1,0]
	v_cvt_pk_bf16_f32 v18, v18, v19
	v_cvt_pk_bf16_f32 v19, v20, v21
	v_cvt_pk_bf16_f32 v20, v4, v5
	v_pk_mul_f32 v[4:5], v[24:25], v[0:1] op_sel_hi:[1,0]
	v_permlane32_swap_b32_e32 v42, v44
	v_cvt_pk_bf16_f32 v21, v4, v5
	v_pk_mul_f32 v[4:5], v[6:7], v[0:1] op_sel_hi:[1,0]
	v_pk_mul_f32 v[6:7], v[8:9], v[0:1] op_sel_hi:[1,0]
	v_cvt_pk_bf16_f32 v4, v4, v5
	v_cvt_pk_bf16_f32 v5, v6, v7
	v_pk_mul_f32 v[6:7], v[26:27], v[0:1] op_sel_hi:[1,0]
	v_pk_mul_f32 v[8:9], v[28:29], v[0:1] op_sel_hi:[1,0]
	v_cvt_pk_bf16_f32 v6, v6, v7
	v_cvt_pk_bf16_f32 v7, v8, v9
	v_pk_mul_f32 v[8:9], v[10:11], v[0:1] op_sel_hi:[1,0]
	v_permlane32_swap_b32_e32 v43, v45
	v_cvt_pk_bf16_f32 v10, v8, v9
	v_pk_mul_f32 v[8:9], v[12:13], v[0:1] op_sel_hi:[1,0]
	v_pk_mul_f32 v[12:13], v[32:33], v[0:1] op_sel_hi:[1,0]
	v_cvt_pk_bf16_f32 v11, v8, v9
	v_pk_mul_f32 v[8:9], v[30:31], v[0:1] op_sel_hi:[1,0]
	v_permlane32_swap_b32_e32 v18, v20
	v_cvt_pk_bf16_f32 v8, v8, v9
	v_cvt_pk_bf16_f32 v9, v12, v13
	v_pk_mul_f32 v[12:13], v[14:15], v[0:1] op_sel_hi:[1,0]
	v_pk_mul_f32 v[14:15], v[16:17], v[0:1] op_sel_hi:[1,0]
	v_cvt_pk_bf16_f32 v12, v12, v13
	v_cvt_pk_bf16_f32 v13, v14, v15
	v_lshl_add_u64 v[14:15], v[46:47], 0, s[2:3]
	s_mov_b32 s2, 0x10000
	v_add_co_u32_e32 v16, vcc, s2, v46
	v_permlane32_swap_b32_e32 v6, v8
	v_permlane32_swap_b32_e32 v7, v9
	s_mov_b64 s[2:3], 0x10440
	v_permlane32_swap_b32_e32 v19, v21
	v_addc_co_u32_e32 v17, vcc, 0, v47, vcc
	global_store_dwordx4 v[14:15], v[6:9], off offset:32
	v_permlane32_swap_b32_e32 v2, v4
	s_nop 0
	v_lshl_add_u64 v[6:7], v[46:47], 0, s[2:3]
	v_permlane32_swap_b32_e32 v3, v5
	v_permlane32_swap_b32_e32 v10, v12
	v_permlane32_swap_b32_e32 v11, v13
	global_store_dwordx4 v[46:47], v[50:53], off offset:1024
	global_store_dwordx4 v[46:47], v[42:45], off offset:1120
	global_store_dwordx4 v[16:17], v[18:21], off offset:1024
	global_store_dwordx4 v[16:17], v[2:5], off offset:1088
	global_store_dwordx4 v[6:7], v[10:13], off offset:32
	s_waitcnt vmcnt(0)
	s_barrier
	s_cbranch_scc1 .LBB0_322

; DI void gqa_block2(unsigned char* lds, const int tid, const u16* __restrict__ q, const unsigned char* __restrict__ kimg, ...
;     ...
;     const unsigned char* sk = lds + (t & 3) * 16384;
;     const unsigned char* sv = sk + 8192;
; #pragma unroll
;     for (int s2 = 0; s2 < 2; ++s2) {
;       f32x16 sc[2];
; #pragma unroll
;       for (int i = 0; i < 16; ++i) { sc[0][i] = 0.f; sc[1][i] = 0.f; }
;       bf16x8 ak[4];
; #pragma unroll
;       for (int ks = 0; ks < 4; ++ks) ak[ks] = *(const bf16x8*)(sk + s2 * 4096 + koff + (((ks * 2 + hl) ^ swk) << 4));
; #pragma unroll
;       for (int ks = 0; ks < 4; ++ks) sc[0] = __builtin_amdgcn_mfma_f32_32x32x16_bf16(ak[ks], bq[0][ks], sc[0], 0, 0, 0);
; #pragma unroll
;       for (int ks = 0; ks < 4; ++ks) sc[1] = __builtin_amdgcn_mfma_f32_32x32x16_bf16(ak[ks], bq[1][ks], sc[1], 0, 0, 0);
;       u32x4 a0[2], a1[2];
; #pragma unroll
;       for (int kb = 0; kb < 2; ++kb) {
;         const u32x2 x0 = *(const u32x2*)(sv + voff + (((s2 * 4 + kb * 2 + 0) ^ swk) << 4));
;         const u32x2 x1 = *(const u32x2*)(sv + voff + (((s2 * 4 + kb * 2 + 1) ^ swk) << 4));
;         const u32x2 y0 = *(const u32x2*)(sv + 4096 + voff + (((s2 * 4 + kb * 2 + 0) ^ swk) << 4));
;         const u32x2 y1 = *(const u32x2*)(sv + 4096 + voff + (((s2 * 4 + kb * 2 + 1) ^ swk) << 4));
;         a0[kb][0] = x0[0]; a0[kb][1] = x0[1]; a0[kb][2] = x1[0]; a0[kb][3] = x1[1];
;         a1[kb][0] = y0[0]; a1[kb][1] = y0[1]; a1[kb][2] = y1[0]; a1[kb][3] = y1[1];
;       }
; #pragma unroll
;       for (int qt = 0; qt < 2; ++qt) {
; #pragma unroll
;         for (int i = 0; i < 16; i += 2) {
;           f2_t x = {sc[qt][i], sc[qt][i + 1]};
;           x = x * c2 + m2;
;           const f2_t e = {__builtin_amdgcn_exp2f(x[0]), __builtin_amdgcn_exp2f(x[1])};
;           sc[qt][i] = e[0]; sc[qt][i + 1] = e[1];
;           ls[qt] += e;
;         }
.LBB0_320:
	v_bfe_u32 v212, v149, 1, 3
	v_lshlrev_b32_e32 v213, 7, v149
	v_add_u32_e32 v214, 0, v235
	v_xor_b32_e32 v214, v214, v212
	v_lshl_add_u32 v160, v214, 4, v213
	v_add_u32_e32 v214, 2, v235
	v_xor_b32_e32 v214, v214, v212
	v_lshl_add_u32 v161, v214, 4, v213
	v_add_u32_e32 v214, 4, v235
	v_xor_b32_e32 v214, v214, v212
	v_lshl_add_u32 v162, v214, 4, v213
	v_add_u32_e32 v214, 6, v235
	v_xor_b32_e32 v214, v214, v212
	v_lshl_add_u32 v163, v214, 4, v213
	v_lshl_add_u32 v215, v235, 3, v213
	v_add_u32_e32 v215, 0x2000, v215
	v_xor_b32_e32 v214, 0, v212
	v_lshl_add_u32 v192, v214, 4, v215
	v_xor_b32_e32 v214, 1, v212
	v_lshl_add_u32 v193, v214, 4, v215
	v_xor_b32_e32 v214, 2, v212
	v_lshl_add_u32 v194, v214, 4, v215
	v_xor_b32_e32 v214, 3, v212
	v_lshl_add_u32 v195, v214, 4, v215
	v_xor_b32_e32 v214, 4, v212
	v_lshl_add_u32 v196, v214, 4, v215
	v_xor_b32_e32 v214, 5, v212
	v_lshl_add_u32 v197, v214, 4, v215
	v_xor_b32_e32 v214, 6, v212
	v_lshl_add_u32 v198, v214, 4, v215
	v_xor_b32_e32 v214, 7, v212
	v_lshl_add_u32 v199, v214, 4, v215
	v_mov_b32_e32 v200, v160
	v_mov_b32_e32 v201, v161
	v_mov_b32_e32 v202, v162
	v_mov_b32_e32 v203, v163
	v_mov_b32_e32 v176, 0
	v_mov_b32_e32 v177, 0
	v_mov_b32_e32 v178, 0
	v_mov_b32_e32 v179, 0
	v_mov_b32_e32 v180, 0
	v_mov_b32_e32 v181, 0
	v_mov_b32_e32 v182, 0
	v_mov_b32_e32 v183, 0
	v_mov_b32_e32 v188, 0
	v_mov_b32_e32 v189, 0
	v_mov_b32_e32 v190, 0
	v_mov_b32_e32 v191, 0
	s_waitcnt vmcnt(4)
	s_barrier
	ds_read_b128 v[130:133], v200
	ds_read_b128 v[134:137], v201
	ds_read_b128 v[138:141], v202
	ds_read_b128 v[142:145], v203
	s_waitcnt lgkmcnt(0)
	v_mfma_f32_32x32x16_bf16 v[66:81], v[130:133], v[110:113], 0
	v_mfma_f32_32x32x16_bf16 v[66:81], v[134:137], v[106:109], v[66:81]
	v_mfma_f32_32x32x16_bf16 v[66:81], v[138:141], v[102:105], v[66:81]
	v_mfma_f32_32x32x16_bf16 v[66:81], v[142:145], v[98:101], v[66:81]
	s_nop 15
.Lgqa_tile:
	s_add_i32 s3, s2, 0xffff4000
	s_and_b32 s3, s3, 0xc000
	v_add_u32_e32 v204, s3, v192
	v_add_u32_e32 v205, s3, v193
	v_add_u32_e32 v206, s3, v194
	v_add_u32_e32 v207, s3, v195
	v_add_u32_e32 v208, s3, v196
	v_add_u32_e32 v209, s3, v197
	v_add_u32_e32 v210, s3, v198
	v_add_u32_e32 v211, s3, v199
	ds_read_b64 v[168:169], v204
	ds_read_b64 v[172:173], v204 offset:4096
	ds_read_b64 v[170:171], v205
	ds_read_b64 v[174:175], v205 offset:4096
	v_fma_f32 v66, v66, s94, v146
	v_fma_f32 v67, v67, s94, v147
	v_fma_f32 v68, v68, s94, v146
	v_fma_f32 v69, v69, s94, v147
	v_fma_f32 v70, v70, s94, v146
	v_fma_f32 v71, v71, s94, v147
	v_fma_f32 v72, v72, s94, v146
	v_mfma_f32_32x32x16_bf16 v[18:33], v[176:179], v[188:191], v[18:33]
	v_fma_f32 v73, v73, s94, v147
	v_exp_f32_e32 v66, v66
	v_exp_f32_e32 v67, v67
	v_exp_f32_e32 v68, v68
	v_exp_f32_e32 v69, v69
	v_exp_f32_e32 v70, v70
	v_exp_f32_e32 v71, v71
	v_mfma_f32_32x32x16_bf16 v[2:17], v[180:183], v[188:191], v[2:17]
	ds_read_b64 v[176:177], v206
	ds_read_b64 v[180:181], v206 offset:4096
	ds_read_b64 v[178:179], v207
	ds_read_b64 v[182:183], v207 offset:4096
	v_exp_f32_e32 v72, v72
	v_exp_f32_e32 v73, v73
	v_cvt_pk_bf16_f32 v184, v66, v67
	v_cvt_pk_bf16_f32 v185, v68, v69
	v_cvt_pk_bf16_f32 v186, v70, v71
	v_cvt_pk_bf16_f32 v187, v72, v73
	v_add_f32_e32 v156, v66, v156
	v_mfma_f32_32x32x16_bf16 v[82:97], v[130:133], v[114:117], 0
	v_add_f32_e32 v157, v67, v157
	v_add_f32_e32 v156, v68, v156
	v_add_f32_e32 v157, v69, v157
	v_add_f32_e32 v156, v70, v156
	v_add_f32_e32 v157, v71, v157
	v_add_f32_e32 v156, v72, v156
	v_add_f32_e32 v157, v73, v157
	v_mfma_f32_32x32x16_bf16 v[82:97], v[134:137], v[118:121], v[82:97]
	v_fma_f32 v74, v74, s94, v146
	v_fma_f32 v75, v75, s94, v147
	v_fma_f32 v76, v76, s94, v146
	v_fma_f32 v77, v77, s94, v147
	v_fma_f32 v78, v78, s94, v146
	v_fma_f32 v79, v79, s94, v147
	v_fma_f32 v80, v80, s94, v146
	v_mfma_f32_32x32x16_bf16 v[82:97], v[138:141], v[122:125], v[82:97]
	v_fma_f32 v81, v81, s94, v147
	v_exp_f32_e32 v74, v74
	v_exp_f32_e32 v75, v75
	v_exp_f32_e32 v76, v76
	v_exp_f32_e32 v77, v77
	v_exp_f32_e32 v78, v78
	v_exp_f32_e32 v79, v79
	v_mfma_f32_32x32x16_bf16 v[82:97], v[142:145], v[126:129], v[82:97]
	ds_read_b128 v[130:133], v200 offset:4096
	ds_read_b128 v[134:137], v201 offset:4096
	ds_read_b128 v[138:141], v202 offset:4096
	ds_read_b128 v[142:145], v203 offset:4096
	v_exp_f32_e32 v80, v80
	v_exp_f32_e32 v81, v81
	v_cvt_pk_bf16_f32 v188, v74, v75
	v_cvt_pk_bf16_f32 v189, v76, v77
	v_cvt_pk_bf16_f32 v190, v78, v79
	v_cvt_pk_bf16_f32 v191, v80, v81
	v_add_f32_e32 v156, v74, v156
	s_waitcnt lgkmcnt(8)
	v_mfma_f32_32x32x16_bf16 v[50:65], v[168:171], v[184:187], v[50:65]
	v_add_f32_e32 v157, v75, v157
	v_add_f32_e32 v156, v76, v156
	v_add_f32_e32 v157, v77, v157
	v_add_f32_e32 v156, v78, v156
	v_add_f32_e32 v157, v79, v157
	v_add_f32_e32 v156, v80, v156
	v_add_f32_e32 v157, v81, v157
	v_mfma_f32_32x32x16_bf16 v[34:49], v[172:175], v[184:187], v[34:49]
	v_fma_f32 v82, v82, s94, v146
	v_fma_f32 v83, v83, s94, v147
	v_fma_f32 v84, v84, s94, v146
	v_fma_f32 v85, v85, s94, v147
	v_fma_f32 v86, v86, s94, v146
	v_fma_f32 v87, v87, s94, v147
	v_fma_f32 v88, v88, s94, v146
	s_waitcnt lgkmcnt(4)
	v_mfma_f32_32x32x16_bf16 v[50:65], v[176:179], v[188:191], v[50:65]
	v_fma_f32 v89, v89, s94, v147
	v_exp_f32_e32 v82, v82
	v_exp_f32_e32 v83, v83
	v_exp_f32_e32 v84, v84
	v_exp_f32_e32 v85, v85
	v_exp_f32_e32 v86, v86
	v_exp_f32_e32 v87, v87
	v_mfma_f32_32x32x16_bf16 v[34:49], v[180:183], v[188:191], v[34:49]
	v_exp_f32_e32 v88, v88
	v_exp_f32_e32 v89, v89
	v_cvt_pk_bf16_f32 v184, v82, v83
	v_cvt_pk_bf16_f32 v185, v84, v85
	v_cvt_pk_bf16_f32 v186, v86, v87
	v_cvt_pk_bf16_f32 v187, v88, v89
	v_add_f32_e32 v154, v82, v154
	s_waitcnt lgkmcnt(0)
; DI void gqa_block2(unsigned char* lds, const int tid, const u16* __restrict__ q, const unsigned char* __restrict__ kimg, ...
;     ...
;   for (int t = 0; t < 36; ++t) {
;     ...
;     for (int s2 = 0; s2 < 2; ++s2) {
;       f32x16 sc[2];
; #pragma unroll
;       for (int i = 0; i < 16; ++i) { sc[0][i] = 0.f; sc[1][i] = 0.f; }
;       bf16x8 ak[4];
; #pragma unroll
;       for (int ks = 0; ks < 4; ++ks) ak[ks] = *(const bf16x8*)(sk + s2 * 4096 + koff + (((ks * 2 + hl) ^ swk) << 4));
; #pragma unroll
;       for (int ks = 0; ks < 4; ++ks) sc[0] = __builtin_amdgcn_mfma_f32_32x32x16_bf16(ak[ks], bq[0][ks], sc[0], 0, 0, 0);
; #pragma unroll
;       for (int ks = 0; ks < 4; ++ks) sc[1] = __builtin_amdgcn_mfma_f32_32x32x16_bf16(ak[ks], bq[1][ks], sc[1], 0, 0, 0);
;       u32x4 a0[2], a1[2];
; #pragma unroll
;       for (int kb = 0; kb < 2; ++kb) {
;         const u32x2 x0 = *(const u32x2*)(sv + voff + (((s2 * 4 + kb * 2 + 0) ^ swk) << 4));
;         const u32x2 x1 = *(const u32x2*)(sv + voff + (((s2 * 4 + kb * 2 + 1) ^ swk) << 4));
;         const u32x2 y0 = *(const u32x2*)(sv + 4096 + voff + (((s2 * 4 + kb * 2 + 0) ^ swk) << 4));
;         const u32x2 y1 = *(const u32x2*)(sv + 4096 + voff + (((s2 * 4 + kb * 2 + 1) ^ swk) << 4));
;         a0[kb][0] = x0[0]; a0[kb][1] = x0[1]; a0[kb][2] = x1[0]; a0[kb][3] = x1[1];
;         a1[kb][0] = y0[0]; a1[kb][1] = y0[1]; a1[kb][2] = y1[0]; a1[kb][3] = y1[1];
;       }
; #pragma unroll
;       for (int qt = 0; qt < 2; ++qt) {
; #pragma unroll
;         for (int i = 0; i < 16; i += 2) {
;           f2_t x = {sc[qt][i], sc[qt][i + 1]};
;           x = x * c2 + m2;
;           const f2_t e = {__builtin_amdgcn_exp2f(x[0]), __builtin_amdgcn_exp2f(x[1])};
;           sc[qt][i] = e[0]; sc[qt][i + 1] = e[1];
;           ls[qt] += e;
;         }
; #pragma unroll
;         for (int kb = 0; kb < 2; ++kb) {
;           u32x4 pp;
; #pragma unroll
;           for (int j = 0; j < 4; ++j) pp[j] = pk2(sc[qt][kb * 8 + 2 * j], sc[qt][kb * 8 + 2 * j + 1]);
;           const bf16x8 pb = __builtin_bit_cast(bf16x8, pp);
;           o[qt][0] = __builtin_amdgcn_mfma_f32_32x32x16_bf16(__builtin_bit_cast(bf16x8, a0[kb]), pb, o[qt][0], 0, 0, 0);
;           o[qt][1] = __builtin_amdgcn_mfma_f32_32x32x16_bf16(__builtin_bit_cast(bf16x8, a1[kb]), pb, o[qt][1], 0, 0, 0);
;         }
;       }
;     }
;   }
	v_mfma_f32_32x32x16_bf16 v[66:81], v[130:133], v[110:113], 0
	v_add_f32_e32 v155, v83, v155
	v_add_f32_e32 v154, v84, v154
	v_add_f32_e32 v155, v85, v155
	v_add_f32_e32 v154, v86, v154
	v_add_f32_e32 v155, v87, v155
	v_add_f32_e32 v154, v88, v154
	v_add_f32_e32 v155, v89, v155
	v_mfma_f32_32x32x16_bf16 v[66:81], v[134:137], v[106:109], v[66:81]
	v_fma_f32 v90, v90, s94, v146
	v_fma_f32 v91, v91, s94, v147
	v_fma_f32 v92, v92, s94, v146
	v_fma_f32 v93, v93, s94, v147
	v_fma_f32 v94, v94, s94, v146
	v_fma_f32 v95, v95, s94, v147
	v_fma_f32 v96, v96, s94, v146
	v_mfma_f32_32x32x16_bf16 v[66:81], v[138:141], v[102:105], v[66:81]
	v_fma_f32 v97, v97, s94, v147
	v_exp_f32_e32 v90, v90
	v_exp_f32_e32 v91, v91
	v_exp_f32_e32 v92, v92
	v_exp_f32_e32 v93, v93
	v_exp_f32_e32 v94, v94
	v_exp_f32_e32 v95, v95
	v_mfma_f32_32x32x16_bf16 v[66:81], v[142:145], v[98:101], v[66:81]
	v_exp_f32_e32 v96, v96
	v_exp_f32_e32 v97, v97
	v_cvt_pk_bf16_f32 v188, v90, v91
	v_cvt_pk_bf16_f32 v189, v92, v93
	v_cvt_pk_bf16_f32 v190, v94, v95
	v_cvt_pk_bf16_f32 v191, v96, v97
	v_add_f32_e32 v154, v90, v154
	v_mfma_f32_32x32x16_bf16 v[18:33], v[168:171], v[184:187], v[18:33]
	v_add_f32_e32 v155, v91, v155
	v_add_f32_e32 v154, v92, v154
	v_add_f32_e32 v155, v93, v155
	v_add_f32_e32 v154, v94, v154
	v_add_f32_e32 v155, v95, v155
	v_add_f32_e32 v154, v96, v154
	v_add_f32_e32 v155, v97, v155
	v_mfma_f32_32x32x16_bf16 v[2:17], v[172:175], v[184:187], v[2:17]
	ds_read_b64 v[168:169], v208
	ds_read_b64 v[172:173], v208 offset:4096
	ds_read_b64 v[170:171], v209
	ds_read_b64 v[174:175], v209 offset:4096
	v_fma_f32 v66, v66, s94, v146
	v_fma_f32 v67, v67, s94, v147
	v_fma_f32 v68, v68, s94, v146
	v_fma_f32 v69, v69, s94, v147
	v_fma_f32 v70, v70, s94, v146
	v_fma_f32 v71, v71, s94, v147
	v_fma_f32 v72, v72, s94, v146
	v_mfma_f32_32x32x16_bf16 v[18:33], v[176:179], v[188:191], v[18:33]
	v_fma_f32 v73, v73, s94, v147
	v_exp_f32_e32 v66, v66
	v_exp_f32_e32 v67, v67
	v_exp_f32_e32 v68, v68
	v_exp_f32_e32 v69, v69
	v_exp_f32_e32 v70, v70
	v_exp_f32_e32 v71, v71
	v_mfma_f32_32x32x16_bf16 v[2:17], v[180:183], v[188:191], v[2:17]
	ds_read_b64 v[176:177], v210
	ds_read_b64 v[180:181], v210 offset:4096
	ds_read_b64 v[178:179], v211
	ds_read_b64 v[182:183], v211 offset:4096
	v_exp_f32_e32 v72, v72
	v_exp_f32_e32 v73, v73
	v_cvt_pk_bf16_f32 v184, v66, v67
	v_cvt_pk_bf16_f32 v185, v68, v69
	v_cvt_pk_bf16_f32 v186, v70, v71
	v_cvt_pk_bf16_f32 v187, v72, v73
	v_add_f32_e32 v156, v66, v156
	v_mfma_f32_32x32x16_bf16 v[82:97], v[130:133], v[114:117], 0
	v_add_f32_e32 v157, v67, v157
	v_add_f32_e32 v156, v68, v156
	v_add_f32_e32 v157, v69, v157
	v_add_f32_e32 v156, v70, v156
	v_add_f32_e32 v157, v71, v157
	v_add_f32_e32 v156, v72, v156
	v_add_f32_e32 v157, v73, v157
	v_mfma_f32_32x32x16_bf16 v[82:97], v[134:137], v[118:121], v[82:97]
	v_fma_f32 v74, v74, s94, v146
	v_fma_f32 v75, v75, s94, v147
	v_fma_f32 v76, v76, s94, v146
	v_fma_f32 v77, v77, s94, v147
	v_fma_f32 v78, v78, s94, v146
	v_fma_f32 v79, v79, s94, v147
	v_fma_f32 v80, v80, s94, v146
	v_mfma_f32_32x32x16_bf16 v[82:97], v[138:141], v[122:125], v[82:97]
	v_fma_f32 v81, v81, s94, v147
	v_exp_f32_e32 v74, v74
	v_exp_f32_e32 v75, v75
	v_exp_f32_e32 v76, v76
	v_exp_f32_e32 v77, v77
	v_exp_f32_e32 v78, v78
	v_exp_f32_e32 v79, v79
	v_mfma_f32_32x32x16_bf16 v[82:97], v[142:145], v[126:129], v[82:97]
	s_cmp_lt_u32 s13, 34
	s_cbranch_scc1 .Lgqa_w2
	s_cmp_eq_u32 s13, 35
	s_cbranch_scc1 .Lgqa_nodma
	s_waitcnt vmcnt(0)
	s_branch .Lgqa_bar
.Lgqa_w2:
	s_waitcnt vmcnt(2)
.Lgqa_bar:
	s_barrier
	s_cmp_gt_u32 s13, 32
	s_cbranch_scc1 .Lgqa_nodma
	s_and_b32 s3, s2, 0xc000
	v_add_u32_e32 v212, s3, v166
	s_mov_b32 s4, 0xffb80000
	v_add_u32_e32 v213, 0x2000, v212
	s_mov_b32 s5, -1
	v_readfirstlane_b32 s3, v212
	v_lshl_add_u64 v[214:215], v[152:153], 0, s[4:5]
	s_mov_b32 m0, s3
	v_readfirstlane_b32 s3, v213
	global_load_lds_dwordx4 v[214:215], off
	s_mov_b32 m0, s3
	s_nop 0
	global_load_lds_dwordx4 v[152:153], off
	v_lshl_add_u64 v[152:153], v[152:153], 0, s[24:25]
; DI unsigned pk2(float a, float b) { f2_t v = {a, b}; bf2_t r = __builtin_convertvector(v, bf2_t); return __builtin_bit_cast(unsigned, r); }
; DI void gqa_block2(unsigned char* lds, const int tid, const u16* __restrict__ q, const unsigned char* __restrict__ kimg, ...
;     ...
;       for (int kb = 0; kb < 2; ++kb) {
;         const u32x2 x0 = *(const u32x2*)(sv + voff + (((s2 * 4 + kb * 2 + 0) ^ swk) << 4));
;         const u32x2 x1 = *(const u32x2*)(sv + voff + (((s2 * 4 + kb * 2 + 1) ^ swk) << 4));
;         const u32x2 y0 = *(const u32x2*)(sv + 4096 + voff + (((s2 * 4 + kb * 2 + 0) ^ swk) << 4));
;         const u32x2 y1 = *(const u32x2*)(sv + 4096 + voff + (((s2 * 4 + kb * 2 + 1) ^ swk) << 4));
;         a0[kb][0] = x0[0]; a0[kb][1] = x0[1]; a0[kb][2] = x1[0]; a0[kb][3] = x1[1];
;         a1[kb][0] = y0[0]; a1[kb][1] = y0[1]; a1[kb][2] = y1[0]; a1[kb][3] = y1[1];
;       }
; #pragma unroll
;       for (int qt = 0; qt < 2; ++qt) {
; #pragma unroll
;         for (int i = 0; i < 16; i += 2) {
;           f2_t x = {sc[qt][i], sc[qt][i + 1]};
;           x = x * c2 + m2;
;           const f2_t e = {__builtin_amdgcn_exp2f(x[0]), __builtin_amdgcn_exp2f(x[1])};
;           sc[qt][i] = e[0]; sc[qt][i + 1] = e[1];
;           ls[qt] += e;
;         }
; #pragma unroll
;         for (int kb = 0; kb < 2; ++kb) {
;           u32x4 pp;
; #pragma unroll
;           for (int j = 0; j < 4; ++j) pp[j] = pk2(sc[qt][kb * 8 + 2 * j], sc[qt][kb * 8 + 2 * j + 1]);
;           const bf16x8 pb = __builtin_bit_cast(bf16x8, pp);
;           o[qt][0] = __builtin_amdgcn_mfma_f32_32x32x16_bf16(__builtin_bit_cast(bf16x8, a0[kb]), pb, o[qt][0], 0, 0, 0);
;           o[qt][1] = __builtin_amdgcn_mfma_f32_32x32x16_bf16(__builtin_bit_cast(bf16x8, a1[kb]), pb, o[qt][1], 0, 0, 0);
;         }
;       }
;     }
;   }
.Lgqa_nodma:
	s_add_i32 s3, s2, 0xffff8000
	s_and_b32 s3, s3, 0xc000
	v_add_u32_e32 v200, s3, v160
	v_add_u32_e32 v201, s3, v161
	v_add_u32_e32 v202, s3, v162
	v_add_u32_e32 v203, s3, v163
	ds_read_b128 v[130:133], v200
	ds_read_b128 v[134:137], v201
	ds_read_b128 v[138:141], v202
	ds_read_b128 v[142:145], v203
	v_exp_f32_e32 v80, v80
	v_exp_f32_e32 v81, v81
	v_cvt_pk_bf16_f32 v188, v74, v75
	v_cvt_pk_bf16_f32 v189, v76, v77
	v_cvt_pk_bf16_f32 v190, v78, v79
	v_cvt_pk_bf16_f32 v191, v80, v81
	v_add_f32_e32 v156, v74, v156
	s_waitcnt lgkmcnt(8)
	v_mfma_f32_32x32x16_bf16 v[50:65], v[168:171], v[184:187], v[50:65]
	v_add_f32_e32 v157, v75, v157
	v_add_f32_e32 v156, v76, v156
	v_add_f32_e32 v157, v77, v157
	v_add_f32_e32 v156, v78, v156
	v_add_f32_e32 v157, v79, v157
	v_add_f32_e32 v156, v80, v156
	v_add_f32_e32 v157, v81, v157
	v_mfma_f32_32x32x16_bf16 v[34:49], v[172:175], v[184:187], v[34:49]
	v_fma_f32 v82, v82, s94, v146
	v_fma_f32 v83, v83, s94, v147
	v_fma_f32 v84, v84, s94, v146
	v_fma_f32 v85, v85, s94, v147
	v_fma_f32 v86, v86, s94, v146
	v_fma_f32 v87, v87, s94, v147
	v_fma_f32 v88, v88, s94, v146
	s_waitcnt lgkmcnt(4)
	v_mfma_f32_32x32x16_bf16 v[50:65], v[176:179], v[188:191], v[50:65]
	v_fma_f32 v89, v89, s94, v147
	v_exp_f32_e32 v82, v82
	v_exp_f32_e32 v83, v83
	v_exp_f32_e32 v84, v84
	v_exp_f32_e32 v85, v85
	v_exp_f32_e32 v86, v86
	v_exp_f32_e32 v87, v87
	v_mfma_f32_32x32x16_bf16 v[34:49], v[180:183], v[188:191], v[34:49]
	v_exp_f32_e32 v88, v88
	v_exp_f32_e32 v89, v89
	v_cvt_pk_bf16_f32 v184, v82, v83
	v_cvt_pk_bf16_f32 v185, v84, v85
	v_cvt_pk_bf16_f32 v186, v86, v87
	v_cvt_pk_bf16_f32 v187, v88, v89
	v_add_f32_e32 v154, v82, v154
	s_waitcnt lgkmcnt(0)
	v_mfma_f32_32x32x16_bf16 v[66:81], v[130:133], v[110:113], 0
	v_add_f32_e32 v155, v83, v155
	v_add_f32_e32 v154, v84, v154
	v_add_f32_e32 v155, v85, v155
	v_add_f32_e32 v154, v86, v154
	v_add_f32_e32 v155, v87, v155
	v_add_f32_e32 v154, v88, v154
	v_add_f32_e32 v155, v89, v155
	v_mfma_f32_32x32x16_bf16 v[66:81], v[134:137], v[106:109], v[66:81]
	v_fma_f32 v90, v90, s94, v146
	v_fma_f32 v91, v91, s94, v147
	v_fma_f32 v92, v92, s94, v146
	v_fma_f32 v93, v93, s94, v147
	v_fma_f32 v94, v94, s94, v146
	v_fma_f32 v95, v95, s94, v147
	v_fma_f32 v96, v96, s94, v146
	v_mfma_f32_32x32x16_bf16 v[66:81], v[138:141], v[102:105], v[66:81]
	v_fma_f32 v97, v97, s94, v147
	v_exp_f32_e32 v90, v90
	v_exp_f32_e32 v91, v91
	v_exp_f32_e32 v92, v92
	v_exp_f32_e32 v93, v93
	v_exp_f32_e32 v94, v94
	v_exp_f32_e32 v95, v95
	v_mfma_f32_32x32x16_bf16 v[66:81], v[142:145], v[98:101], v[66:81]
	v_exp_f32_e32 v96, v96
	v_exp_f32_e32 v97, v97
	v_cvt_pk_bf16_f32 v188, v90, v91
	v_cvt_pk_bf16_f32 v189, v92, v93
	v_cvt_pk_bf16_f32 v190, v94, v95
	v_cvt_pk_bf16_f32 v191, v96, v97
	v_add_f32_e32 v154, v90, v154
	v_mfma_f32_32x32x16_bf16 v[18:33], v[168:171], v[184:187], v[18:33]
	v_add_f32_e32 v155, v91, v155
	v_add_f32_e32 v154, v92, v154
	v_add_f32_e32 v155, v93, v155
	v_add_f32_e32 v154, v94, v154
	v_add_f32_e32 v155, v95, v155
	v_add_f32_e32 v154, v96, v154
	v_add_f32_e32 v155, v97, v155
	v_mfma_f32_32x32x16_bf16 v[2:17], v[172:175], v[184:187], v[2:17]
	s_add_i32 s13, s13, 1
	s_addk_i32 s2, 0x4000
	s_cmp_lt_u32 s13, 36
	s_cbranch_scc1 .Lgqa_tile
	v_mfma_f32_32x32x16_bf16 v[18:33], v[176:179], v[188:191], v[18:33]
	v_mfma_f32_32x32x16_bf16 v[2:17], v[180:183], v[188:191], v[2:17]
	v_add_f32_e32 v0, v156, v157
	v_mov_b32_e32 v66, v154
	v_mov_b32_e32 v67, v155
	s_lshl_b64 s[2:3], s[40:41], 11
	v_readlane_b32 s4, v255, 10
	s_add_u32 s2, s4, s2
	v_readlane_b32 s4, v255, 11
	s_addc_u32 s3, s4, s3
	s_add_u32 s2, s2, s38
	s_addc_u32 s3, s3, s39
	s_add_i32 s12, s12, s88
	s_cmpk_gt_i32 s12, 0xff
	s_branch .LBB0_317
